# rwkv_prep: 8-way partial-sum reduction of the value-residual stage rewritten with batched LDS reads (same add order)
# baseline (speedup 1.0000x reference)
; DEVI void rwkv_prep(const Params& p, int l, unsigned char* smem, int item) {
;     ...
; #pragma unroll 8
;             for (int cc = 0; cc < 64; ++cc) {
;                 const float w = v1[(cp * 64 + cc) * 64 + m]; const f32x4* lp = (const f32x4*)(sVx + (cp * 64 + cc) * 16);
; #pragma unroll
;                 for (int q = 0; q < 4; ++q) { const f32x4 x = lp[q]; ma[4 * q] += x[0] * w; ma[4 * q + 1] += x[1] * w; ma[4 * q + 2] += x[2] * w; ma[4 * q + 3] += x[3] * w; }
;             }
.LBB0_400:
	v_lshl_add_u64 v[244:245], v[76:77], 0, s[8:9]
	global_load_dword v220, v[244:245], off
	global_load_dword v221, v[244:245], off offset:256
	global_load_dword v222, v[244:245], off offset:512
	global_load_dword v223, v[244:245], off offset:768
	global_load_dword v224, v[244:245], off offset:1024
	global_load_dword v225, v[244:245], off offset:1280
	global_load_dword v226, v[244:245], off offset:1536
	global_load_dword v227, v[244:245], off offset:1792
	ds_read_b128 v[108:111], v106
	ds_read_b128 v[112:115], v106 offset:16
	ds_read_b128 v[116:119], v106 offset:32
	ds_read_b128 v[120:123], v106 offset:48
	ds_read_b128 v[228:231], v106 offset:64
	ds_read_b128 v[232:235], v106 offset:80
	ds_read_b128 v[236:239], v106 offset:96
	ds_read_b128 v[240:243], v106 offset:112
	v_add_u32_e32 v74, 0x200, v74
	s_add_u32 s8, s8, 0x800
	s_addc_u32 s9, s9, 0
	s_waitcnt vmcnt(7) lgkmcnt(4)
	v_pk_fma_f32 v[0:1], v[220:221], v[108:109], v[0:1] op_sel_hi:[0,1,1]
	v_pk_fma_f32 v[2:3], v[220:221], v[110:111], v[2:3] op_sel_hi:[0,1,1]
	v_pk_fma_f32 v[4:5], v[220:221], v[112:113], v[4:5] op_sel_hi:[0,1,1]
	v_pk_fma_f32 v[6:7], v[220:221], v[114:115], v[6:7] op_sel_hi:[0,1,1]
	v_pk_fma_f32 v[12:13], v[220:221], v[116:117], v[12:13] op_sel_hi:[0,1,1]
	v_pk_fma_f32 v[14:15], v[220:221], v[118:119], v[14:15] op_sel_hi:[0,1,1]
	v_pk_fma_f32 v[8:9], v[220:221], v[120:121], v[8:9] op_sel_hi:[0,1,1]
	v_pk_fma_f32 v[10:11], v[220:221], v[122:123], v[10:11] op_sel_hi:[0,1,1]
	ds_read_b128 v[108:111], v106 offset:128
	ds_read_b128 v[112:115], v106 offset:144
	ds_read_b128 v[116:119], v106 offset:160
	ds_read_b128 v[120:123], v106 offset:176
	s_waitcnt vmcnt(6) lgkmcnt(4)
	v_pk_fma_f32 v[0:1], v[220:221], v[228:229], v[0:1] op_sel:[1,0,0] op_sel_hi:[1,1,1]
	v_pk_fma_f32 v[2:3], v[220:221], v[230:231], v[2:3] op_sel:[1,0,0] op_sel_hi:[1,1,1]
	v_pk_fma_f32 v[4:5], v[220:221], v[232:233], v[4:5] op_sel:[1,0,0] op_sel_hi:[1,1,1]
	v_pk_fma_f32 v[6:7], v[220:221], v[234:235], v[6:7] op_sel:[1,0,0] op_sel_hi:[1,1,1]
	v_pk_fma_f32 v[12:13], v[220:221], v[236:237], v[12:13] op_sel:[1,0,0] op_sel_hi:[1,1,1]
	v_pk_fma_f32 v[14:15], v[220:221], v[238:239], v[14:15] op_sel:[1,0,0] op_sel_hi:[1,1,1]
	v_pk_fma_f32 v[8:9], v[220:221], v[240:241], v[8:9] op_sel:[1,0,0] op_sel_hi:[1,1,1]
	v_pk_fma_f32 v[10:11], v[220:221], v[242:243], v[10:11] op_sel:[1,0,0] op_sel_hi:[1,1,1]
	ds_read_b128 v[228:231], v106 offset:192
	ds_read_b128 v[232:235], v106 offset:208
	ds_read_b128 v[236:239], v106 offset:224
	ds_read_b128 v[240:243], v106 offset:240
	s_waitcnt vmcnt(5) lgkmcnt(4)
	v_pk_fma_f32 v[0:1], v[222:223], v[108:109], v[0:1] op_sel_hi:[0,1,1]
	v_pk_fma_f32 v[2:3], v[222:223], v[110:111], v[2:3] op_sel_hi:[0,1,1]
	v_pk_fma_f32 v[4:5], v[222:223], v[112:113], v[4:5] op_sel_hi:[0,1,1]
	v_pk_fma_f32 v[6:7], v[222:223], v[114:115], v[6:7] op_sel_hi:[0,1,1]
	v_pk_fma_f32 v[12:13], v[222:223], v[116:117], v[12:13] op_sel_hi:[0,1,1]
	v_pk_fma_f32 v[14:15], v[222:223], v[118:119], v[14:15] op_sel_hi:[0,1,1]
	v_pk_fma_f32 v[8:9], v[222:223], v[120:121], v[8:9] op_sel_hi:[0,1,1]
	v_pk_fma_f32 v[10:11], v[222:223], v[122:123], v[10:11] op_sel_hi:[0,1,1]
	ds_read_b128 v[108:111], v106 offset:256
	ds_read_b128 v[112:115], v106 offset:272
	ds_read_b128 v[116:119], v106 offset:288
	ds_read_b128 v[120:123], v106 offset:304
	s_waitcnt vmcnt(4) lgkmcnt(4)
	v_pk_fma_f32 v[0:1], v[222:223], v[228:229], v[0:1] op_sel:[1,0,0] op_sel_hi:[1,1,1]
	v_pk_fma_f32 v[2:3], v[222:223], v[230:231], v[2:3] op_sel:[1,0,0] op_sel_hi:[1,1,1]
	v_pk_fma_f32 v[4:5], v[222:223], v[232:233], v[4:5] op_sel:[1,0,0] op_sel_hi:[1,1,1]
	v_pk_fma_f32 v[6:7], v[222:223], v[234:235], v[6:7] op_sel:[1,0,0] op_sel_hi:[1,1,1]
	v_pk_fma_f32 v[12:13], v[222:223], v[236:237], v[12:13] op_sel:[1,0,0] op_sel_hi:[1,1,1]
	v_pk_fma_f32 v[14:15], v[222:223], v[238:239], v[14:15] op_sel:[1,0,0] op_sel_hi:[1,1,1]
	v_pk_fma_f32 v[8:9], v[222:223], v[240:241], v[8:9] op_sel:[1,0,0] op_sel_hi:[1,1,1]
	v_pk_fma_f32 v[10:11], v[222:223], v[242:243], v[10:11] op_sel:[1,0,0] op_sel_hi:[1,1,1]
	ds_read_b128 v[228:231], v106 offset:320
	ds_read_b128 v[232:235], v106 offset:336
	ds_read_b128 v[236:239], v106 offset:352
	ds_read_b128 v[240:243], v106 offset:368
	s_waitcnt vmcnt(3) lgkmcnt(4)
; DEVI void rwkv_prep(const Params& p, int l, unsigned char* smem, int item) {
;     ...
; #pragma unroll 8
;             for (int cc = 0; cc < 64; ++cc) {
;                 const float w = v1[(cp * 64 + cc) * 64 + m]; const f32x4* lp = (const f32x4*)(sVx + (cp * 64 + cc) * 16);
; #pragma unroll
;                 for (int q = 0; q < 4; ++q) { const f32x4 x = lp[q]; ma[4 * q] += x[0] * w; ma[4 * q + 1] += x[1] * w; ma[4 * q + 2] += x[2] * w; ma[4 * q + 3] += x[3] * w; }
;             }
;             float* sP = sMid + 64 * 16;
; #pragma unroll
;             for (int q = 0; q < 4; ++q) *(f32x4*)(sP + (cp * 64 + m) * 16 + 4 * q) = (f32x4){ma[4 * q], ma[4 * q + 1], ma[4 * q + 2], ma[4 * q + 3]};
;             __syncthreads();
;             for (int e = tid; e < 1024; e += NT) {
;                 float a = 0.f;
; #pragma unroll
;                 for (int k = 0; k < 8; ++k) a += sP[k * 1024 + e];
;                 sMid[e] = a;
;             }
	v_pk_fma_f32 v[0:1], v[224:225], v[108:109], v[0:1] op_sel_hi:[0,1,1]
	v_pk_fma_f32 v[2:3], v[224:225], v[110:111], v[2:3] op_sel_hi:[0,1,1]
	v_pk_fma_f32 v[4:5], v[224:225], v[112:113], v[4:5] op_sel_hi:[0,1,1]
	v_pk_fma_f32 v[6:7], v[224:225], v[114:115], v[6:7] op_sel_hi:[0,1,1]
	v_pk_fma_f32 v[12:13], v[224:225], v[116:117], v[12:13] op_sel_hi:[0,1,1]
	v_pk_fma_f32 v[14:15], v[224:225], v[118:119], v[14:15] op_sel_hi:[0,1,1]
	v_pk_fma_f32 v[8:9], v[224:225], v[120:121], v[8:9] op_sel_hi:[0,1,1]
	v_pk_fma_f32 v[10:11], v[224:225], v[122:123], v[10:11] op_sel_hi:[0,1,1]
	ds_read_b128 v[108:111], v106 offset:384
	ds_read_b128 v[112:115], v106 offset:400
	ds_read_b128 v[116:119], v106 offset:416
	ds_read_b128 v[120:123], v106 offset:432
	s_waitcnt vmcnt(2) lgkmcnt(4)
	v_pk_fma_f32 v[0:1], v[224:225], v[228:229], v[0:1] op_sel:[1,0,0] op_sel_hi:[1,1,1]
	v_pk_fma_f32 v[2:3], v[224:225], v[230:231], v[2:3] op_sel:[1,0,0] op_sel_hi:[1,1,1]
	v_pk_fma_f32 v[4:5], v[224:225], v[232:233], v[4:5] op_sel:[1,0,0] op_sel_hi:[1,1,1]
	v_pk_fma_f32 v[6:7], v[224:225], v[234:235], v[6:7] op_sel:[1,0,0] op_sel_hi:[1,1,1]
	v_pk_fma_f32 v[12:13], v[224:225], v[236:237], v[12:13] op_sel:[1,0,0] op_sel_hi:[1,1,1]
	v_pk_fma_f32 v[14:15], v[224:225], v[238:239], v[14:15] op_sel:[1,0,0] op_sel_hi:[1,1,1]
	v_pk_fma_f32 v[8:9], v[224:225], v[240:241], v[8:9] op_sel:[1,0,0] op_sel_hi:[1,1,1]
	v_pk_fma_f32 v[10:11], v[224:225], v[242:243], v[10:11] op_sel:[1,0,0] op_sel_hi:[1,1,1]
	ds_read_b128 v[228:231], v106 offset:448
	ds_read_b128 v[232:235], v106 offset:464
	ds_read_b128 v[236:239], v106 offset:480
	ds_read_b128 v[240:243], v106 offset:496
	s_waitcnt vmcnt(1) lgkmcnt(4)
	v_pk_fma_f32 v[0:1], v[226:227], v[108:109], v[0:1] op_sel_hi:[0,1,1]
	v_pk_fma_f32 v[2:3], v[226:227], v[110:111], v[2:3] op_sel_hi:[0,1,1]
	v_pk_fma_f32 v[4:5], v[226:227], v[112:113], v[4:5] op_sel_hi:[0,1,1]
	v_pk_fma_f32 v[6:7], v[226:227], v[114:115], v[6:7] op_sel_hi:[0,1,1]
	v_pk_fma_f32 v[12:13], v[226:227], v[116:117], v[12:13] op_sel_hi:[0,1,1]
	v_pk_fma_f32 v[14:15], v[226:227], v[118:119], v[14:15] op_sel_hi:[0,1,1]
	v_pk_fma_f32 v[8:9], v[226:227], v[120:121], v[8:9] op_sel_hi:[0,1,1]
	v_pk_fma_f32 v[10:11], v[226:227], v[122:123], v[10:11] op_sel_hi:[0,1,1]
	s_waitcnt vmcnt(0) lgkmcnt(0)
	v_pk_fma_f32 v[0:1], v[226:227], v[228:229], v[0:1] op_sel:[1,0,0] op_sel_hi:[1,1,1]
	v_pk_fma_f32 v[2:3], v[226:227], v[230:231], v[2:3] op_sel:[1,0,0] op_sel_hi:[1,1,1]
	v_pk_fma_f32 v[4:5], v[226:227], v[232:233], v[4:5] op_sel:[1,0,0] op_sel_hi:[1,1,1]
	v_pk_fma_f32 v[6:7], v[226:227], v[234:235], v[6:7] op_sel:[1,0,0] op_sel_hi:[1,1,1]
	v_pk_fma_f32 v[12:13], v[226:227], v[236:237], v[12:13] op_sel:[1,0,0] op_sel_hi:[1,1,1]
	v_pk_fma_f32 v[14:15], v[226:227], v[238:239], v[14:15] op_sel:[1,0,0] op_sel_hi:[1,1,1]
	v_pk_fma_f32 v[8:9], v[226:227], v[240:241], v[8:9] op_sel:[1,0,0] op_sel_hi:[1,1,1]
	v_pk_fma_f32 v[10:11], v[226:227], v[242:243], v[10:11] op_sel:[1,0,0] op_sel_hi:[1,1,1]
	s_cmpk_eq_i32 s8, 0x4000
	v_add_u32_e32 v106, 0x200, v106
	s_cbranch_scc0 .LBB0_400
	s_movk_i32 s0, 0x400
	v_cmp_gt_i32_e32 vcc, s0, v16
	ds_write_b128 v83, v[0:3] offset:53248
	ds_write_b128 v83, v[4:7] offset:53264
	ds_write_b128 v83, v[12:15] offset:53280
	ds_write_b128 v83, v[8:11] offset:53296
	s_waitcnt lgkmcnt(0)
	s_barrier
	s_and_saveexec_b64 s[68:69], vcc
	s_cbranch_execz .LBB0_411
	v_lshlrev_b32_e32 v0, 2, v16
	ds_read2st64_b32 v[2:3], v0 offset0:208 offset1:216
	ds_read2st64_b32 v[4:5], v0 offset0:224 offset1:232
	ds_read2st64_b32 v[6:7], v0 offset0:240 offset1:248
	v_add_u32_e32 v1, 0x10000, v0
	ds_read2st64_b32 v[8:9], v1 offset1:8
	ds_read2st64_b32 v[10:11], v1 offset0:16 offset1:24
	ds_read2st64_b32 v[12:13], v1 offset0:32 offset1:40
	ds_read2st64_b32 v[14:15], v1 offset0:48 offset1:56
	ds_read2st64_b32 v[106:107], v1 offset0:64 offset1:72
	s_waitcnt lgkmcnt(7)
	v_pk_add_f32 v[2:3], v[2:3], 0 op_sel_hi:[1,0]
	s_waitcnt lgkmcnt(6)
	v_pk_add_f32 v[2:3], v[2:3], v[4:5]
	s_waitcnt lgkmcnt(5)
	v_pk_add_f32 v[2:3], v[2:3], v[6:7]
	s_waitcnt lgkmcnt(4)
	v_pk_add_f32 v[2:3], v[2:3], v[8:9]
	s_waitcnt lgkmcnt(3)
	v_pk_add_f32 v[2:3], v[2:3], v[10:11]
	s_waitcnt lgkmcnt(2)
	v_pk_add_f32 v[2:3], v[2:3], v[12:13]
	s_waitcnt lgkmcnt(1)
	v_pk_add_f32 v[2:3], v[2:3], v[14:15]
	s_waitcnt lgkmcnt(0)
	v_pk_add_f32 v[2:3], v[2:3], v[106:107]
	ds_write2st64_b32 v0, v2, v3 offset0:192 offset1:200
